# v44 + same row-dependent 16-B chunk-pair LDS swizzle applied to hgrn_r1's five 128x144-B tiles (row-pair writers and MFMA fragment readers), bit-identical results
# speedup vs baseline: 1.0022x; 1.0022x over previous
; #define LAS __attribute__((address_space(3)))
; #define GAS __attribute__((address_space(1)))
; #define ARGP(i) ((const GAS float*)ldptr(ptab, (i)))
; __device__ __forceinline__ void hgrn_r1(const GAS bf16* proj, GAS float* RU, GAS float* RD, int TOKG, unsigned char* lds, int tid, int lane, int wave, int bid, int G) {
;     LAS unsigned char* L = (LAS unsigned char*)lds;
;     constexpr int KSET = 128 * HS + 512, VSET = 128 * HS + 4096, VS0 = 2 * KSET;
;     static_assert(VS0 + 3 * VSET <= 128 * 1024, "r1 LDS map");
;     const int nruns = (TOKG / SEQ) * 16 * (128 / RUNC);
;     const int fr = lane & 15, fq = lane >> 4;
;     unsigned rg[8], rv[8];
;     unsigned voff[8];
; #pragma unroll
;     for (int i = 0; i < 8; ++i) voff[i] = (unsigned)((wave * 8 + i) * (PW * 2) + lane * 4);
;     const __amdgpu_buffer_rsrc_t prs = __builtin_amdgcn_make_buffer_rsrc((void*)proj, 0, (int)((size_t)TOKG * PW * 2), 0x00020000);
; __global__ void __launch_bounds__(512, 2) fwd(Args a) {
;     ...
;             const Ctx c = load_ctx(ptab);
;             if (__builtin_amdgcn_readfirstlane(c.tid) >= 256) __builtin_amdgcn_s_setprio(1);
;             if (c.even) {
;                 attn_mfma(c.proj, c.xn, (GAS float*)(c.xn + (size_t)c.TOKG * 3072), c.TOKG, ARGP(4) + c.j * 64, ARGP(5) + c.j * 64, ARGP(7), lds, c.tid, c.lane, c.wave, c.bid, c.G);
;             } else {
;                 hgrn_r1(c.proj, (GAS float*)c.xn, (GAS float*)(c.wsb + WS_RD), c.TOKG, lds, c.tid, c.lane, c.wave, c.bid, c.G);
.LBB0_254:
	s_abs_i32 s3, s1
	v_cvt_f32_u32_e32 v0, s3
	s_sub_i32 s8, 0, s3
	s_ashr_i32 s7, s0, 31
	s_abs_i32 s0, s0
	v_rcp_iflag_f32_e32 v0, v0
	s_ashr_i32 s1, s1, 31
	s_xor_b32 s7, s7, s1
	v_and_b32_e32 v41, 63, v178
	v_mul_f32_e32 v0, 0x4f7ffffe, v0
	v_cvt_u32_f32_e32 v0, v0
	s_nop 0
	v_readfirstlane_b32 s9, v0
	s_mul_i32 s8, s8, s9
	s_mul_hi_u32 s8, s9, s8
	s_add_i32 s9, s9, s8
	s_mul_hi_u32 s8, s0, s9
	s_mul_i32 s10, s8, s3
	s_sub_i32 s0, s0, s10
	s_add_i32 s11, s8, 1
	s_sub_i32 s10, s0, s3
	s_cmp_ge_u32 s0, s3
	s_cselect_b32 s8, s11, s8
	s_cselect_b32 s0, s10, s0
	s_add_i32 s10, s8, 1
	s_cmp_ge_u32 s0, s3
	s_cselect_b32 s0, s10, s8
	s_lshr_b32 s8, s9, 17
	s_xor_b32 s0, s0, s7
	s_mul_i32 s9, s8, s3
	s_sub_i32 s0, s0, s7
	s_sub_i32 s7, 0x8000, s9
	s_add_i32 s9, s8, 1
	s_sub_i32 s10, s7, s3
	s_cmp_ge_u32 s7, s3
	s_cselect_b32 s8, s9, s8
	s_cselect_b32 s7, s10, s7
	s_add_i32 s9, s8, 1
	s_cmp_ge_u32 s7, s3
	s_cselect_b32 s3, s9, s8
	s_xor_b32 s3, s3, s1
	s_sub_i32 s34, s3, s1
	s_ashr_i32 s28, s6, 6
	s_add_u32 s22, s4, 0x1800000
	s_addc_u32 s23, s5, 0
	s_mul_i32 s3, s34, 0x5000
	s_mul_hi_i32 s1, s34, 0x5000
	s_add_u32 s24, s22, s3
	s_addc_u32 s25, s23, s1
	s_bitcmp1_b32 s0, 0
	s_cselect_b64 s[8:9], -1, 0
	s_mov_b64 s[0:1], -1
	s_and_b64 vcc, exec, s[8:9]
	s_cbranch_vccz .LBB0_270
	s_ashr_i32 s0, s34, 31
	s_lshr_b32 s0, s0, 19
	s_add_i32 s0, s34, s0
	s_ashr_i32 s0, s0, 13
	s_lshl_b32 s3, s0, 7
	s_cmp_ge_i32 s2, s3
	s_cbranch_scc1 .LBB0_269
	v_and_b32_e32 v4, 15, v178
	s_lshl_b32 s29, s28, 4
	v_lshlrev_b32_e32 v0, 2, v41
	s_lshl_b32 s30, s28, 9
	v_or_b32_e32 v1, s29, v4
	v_lshl_or_b32 v70, s28, 17, v0
	s_lshl_b32 s46, s34, 14
	s_and_b32 s45, s23, 0xffff
	s_add_i32 s0, s30, 0
	v_lshlrev_b32_e32 v0, 3, v41
	s_movk_i32 s26, 0x120
	v_and_b32_e32 v112, 48, v178
	v_lshlrev_b32_e32 v2, 7, v1
	v_add_u32_e32 v78, s0, v0
	v_mad_u32_u24 v80, v41, s26, 0
	s_movk_i32 s0, 0xfee8
	s_cmp_lt_u32 s6, 64
	v_add_u32_e32 v40, 0, v112
	s_movk_i32 s6, 0x90
	v_ashrrev_i32_e32 v3, 31, v2
	v_mad_i32_i24 v82, v41, s0, v80
	s_movk_i32 s0, 0x118
	v_mad_u64_u32 v[42:43], s[6:7], v1, s6, v[40:41]
	v_lshl_add_u64 v[2:3], v[2:3], 2, s[24:25]
	v_mov_b32_e32 v1, v113
	v_mad_u32_u24 v83, v41, s0, v82
	s_cselect_b64 s[0:1], -1, 0
	v_lshl_add_u64 v[44:45], v[2:3], 0, v[112:113]
	v_lshl_add_u64 v[2:3], s[4:5], 0, v[0:1]
	s_mov_b64 s[4:5], 0x1410000
	s_cmp_gt_i32 s28, 0
	v_lshl_add_u64 v[46:47], v[2:3], 0, s[4:5]
	s_cselect_b64 s[4:5], -1, 0
	s_cmp_gt_i32 s28, 1
	s_cselect_b64 s[6:7], -1, 0
	s_cmp_gt_i32 s28, 2
	s_cselect_b64 s[8:9], -1, 0
	s_cmp_gt_i32 s28, 3
	s_cselect_b64 s[10:11], -1, 0
	s_cmp_gt_i32 s28, 4
	s_cselect_b64 s[12:13], -1, 0
	s_cmp_gt_i32 s28, 5
	s_cselect_b64 s[14:15], -1, 0
	s_cmp_gt_i32 s28, 6
	s_cselect_b64 s[16:17], -1, 0
	s_cmp_gt_i32 s28, 7
	s_mul_i32 s20, s28, 0x900
	v_add_u32_e32 v87, 0, v0
	v_or_b32_e32 v88, 0x13400, v0
	v_mov_b32_e32 v0, s29
	s_cselect_b64 s[18:19], -1, 0
	v_mul_u32_u24_e32 v43, 0x90, v4
	s_add_i32 s21, s20, 0x9440
	s_add_i32 s20, s20, 0x9400
	v_mad_u32_u24 v0, v41, s26, v0
	v_or_b32_e32 v71, 0x4000, v70
	v_or_b32_e32 v72, 0x8000, v70
	v_or_b32_e32 v73, 0xc000, v70
	v_or_b32_e32 v74, 0x10000, v70
	v_or_b32_e32 v75, 0x14000, v70
	v_or_b32_e32 v76, 0x18000, v70
	v_or_b32_e32 v77, 0x1c000, v70
	s_mov_b32 s44, s22
	v_mul_u32_u24_e32 v79, 0x120, v41
	v_mul_i32_i24_e32 v81, 0xfffffee8, v41
	v_add_u32_e32 v84, 0xb000, v42
	v_add3_u32 v85, s21, v43, v112
	v_add3_u32 v86, s20, v43, v112
	s_add_i32 s30, s30, 0x13400
	v_add_u32_e32 v89, 0xec00, v0
	v_readlane_b32 s31, v236, 14
	v_readlane_b32 s35, v236, 13
	v_readlane_b32 s36, v236, 12
	v_add_u32_e32 v213, 4, v41
	v_and_b32_e32 v213, 8, v213
	v_lshlrev_b32_e32 v213, 1, v213
	v_and_b32_e32 v235, 16, v41
	v_xor_b32_e32 v213, v235, v213
	v_sub_u32_e32 v213, v213, v235
	v_add_u32_e32 v43, v43, v213
	v_add_u32_e32 v42, v42, v213
	v_add_u32_e32 v84, v84, v213
	v_add_u32_e32 v85, v85, v213
	v_add_u32_e32 v86, v86, v213
	v_lshlrev_b32_e32 v234, 1, v41
	v_add_u32_e32 v234, 4, v234
	v_and_b32_e32 v234, 8, v234
	v_lshlrev_b32_e32 v234, 1, v234
	v_mov_b32_e32 v235, s29
	v_and_b32_e32 v235, 16, v235
	v_xor_b32_e32 v234, v234, v235
	v_sub_u32_e32 v234, v234, v235
	v_add_u32_e32 v89, v89, v234
	v_add_u32_e32 v234, s29, v234
	s_mov_b32 s26, s2
	s_branch .LBB0_258

; #define H1_LOAD(u_) do { const int cch_ = (u_) & 127, seq_ = (u_) >> 7; const int so_ = (int)((((size_t)(seq_ >> 4) * SEQ + cch_ * 64) * PW + (seq_ & 15) * 128) * 2); \
;         _Pragma("unroll") for (int i = 0; i < 8; ++i) { rg[i] = __builtin_amdgcn_raw_buffer_load_b32(prs, (int)voff[i], so_ + 4096, 0); rv[i] = __builtin_amdgcn_raw_buffer_load_b32(prs, (int)voff[i], so_ + 8192, 0); } } while (0)
; __device__ __forceinline__ void hgrn_r1(const GAS bf16* proj, GAS float* RU, GAS float* RD, int TOKG, unsigned char* lds, int tid, int lane, int wave, int bid, int G) {
;     ...
;     float f0[8], f1[8], run0, run1;
;     ...
;     for (int run = bid; run < nruns; run += G) {
;         if ((run & (128 / RUNC - 1)) == 128 / RUNC - 1) continue;
;         const int u0 = run * RUNC;
;         __syncthreads();
;         H1_LOAD(u0);
;         f32x4h acc[8];
; #pragma unroll
;         for (int nk = 0; nk < 8; ++nk) acc[nk] = (f32x4h){0.f, 0.f, 0.f, 0.f};
;         float sum0 = 0.f, sum1 = 0.f;
;         R1_P(0, true);
.LBB0_258:
	s_and_b32 s20, s26, 7
	s_cmp_eq_u32 s20, 7
	s_cbranch_scc1 .LBB0_257
	s_lshl_b32 s20, s26, 24
	s_lshl_b32 s21, s26, 20
	s_and_b32 s20, s20, 0x7000000
	s_and_b32 s21, s21, 0xf8000000
	s_or_b32 s20, s21, s20
	s_lshl_b32 s21, s26, 5
	s_and_b32 s21, s21, 0xf00
	s_or_b32 s20, s20, s21
	s_or_b32 s21, s20, 0x1000
	s_barrier
	buffer_load_dword v0, v70, s[44:47], s21 offen
	buffer_load_dword v1, v71, s[44:47], s21 offen
	buffer_load_dword v2, v72, s[44:47], s21 offen
	buffer_load_dword v3, v73, s[44:47], s21 offen
	buffer_load_dword v4, v74, s[44:47], s21 offen
	buffer_load_dword v5, v75, s[44:47], s21 offen
	buffer_load_dword v6, v76, s[44:47], s21 offen
	buffer_load_dword v7, v77, s[44:47], s21 offen
	s_or_b32 s21, s20, 0x2000
	buffer_load_dword v24, v70, s[44:47], s21 offen
	buffer_load_dword v25, v72, s[44:47], s21 offen
	buffer_load_dword v26, v74, s[44:47], s21 offen
	buffer_load_dword v27, v76, s[44:47], s21 offen
	buffer_load_dword v28, v71, s[44:47], s21 offen
	buffer_load_dword v29, v73, s[44:47], s21 offen
	buffer_load_dword v30, v75, s[44:47], s21 offen
	buffer_load_dword v31, v77, s[44:47], s21 offen
	s_or_b32 s21, s20, 0x101000
	s_or_b32 s20, s20, 0x102000
	buffer_load_dword v65, v70, s[44:47], s21 offen
	buffer_load_dword v64, v71, s[44:47], s21 offen
	buffer_load_dword v68, v71, s[44:47], s20 offen
	buffer_load_dword v69, v70, s[44:47], s20 offen
	buffer_load_dword v63, v72, s[44:47], s21 offen
	buffer_load_dword v62, v73, s[44:47], s21 offen
	buffer_load_dword v90, v73, s[44:47], s20 offen
	buffer_load_dword v91, v72, s[44:47], s20 offen
	buffer_load_dword v61, v74, s[44:47], s21 offen
	buffer_load_dword v60, v75, s[44:47], s21 offen
	buffer_load_dword v92, v75, s[44:47], s20 offen
	buffer_load_dword v93, v74, s[44:47], s20 offen
	buffer_load_dword v59, v76, s[44:47], s21 offen
	buffer_load_dword v58, v77, s[44:47], s21 offen
	buffer_load_dword v94, v77, s[44:47], s20 offen
	buffer_load_dword v95, v76, s[44:47], s20 offen
	v_add_u32_e32 v96, v234, v80
	s_andn2_b64 vcc, exec, s[0:1]
	s_waitcnt vmcnt(0)
	v_lshlrev_b32_e32 v8, 16, v0
	v_and_b32_e32 v9, 0xffff0000, v0
	v_lshlrev_b32_e32 v10, 16, v1
	v_and_b32_e32 v11, 0xffff0000, v1
	v_lshlrev_b32_e32 v12, 16, v2
	v_and_b32_e32 v13, 0xffff0000, v2
	v_lshlrev_b32_e32 v16, 16, v4
	v_and_b32_e32 v17, 0xffff0000, v4
	v_lshlrev_b32_e32 v20, 16, v6
	v_and_b32_e32 v21, 0xffff0000, v6
	v_and_b32_e32 v0, 0xffff, v24
	v_and_b32_e32 v2, 0xffff, v26
	v_lshrrev_b32_e32 v4, 16, v24
	v_lshrrev_b32_e32 v6, 16, v26
	v_exp_f32_e32 v24, v8
	v_exp_f32_e32 v26, v9
	v_pk_add_f32 v[8:9], v[8:9], 0 op_sel_hi:[1,0]
	v_lshlrev_b32_e32 v14, 16, v3
	v_pk_add_f32 v[8:9], v[8:9], v[10:11]
	v_and_b32_e32 v15, 0xffff0000, v3
	v_pk_add_f32 v[8:9], v[8:9], v[12:13]
	v_lshlrev_b32_e32 v18, 16, v5
	v_pk_add_f32 v[8:9], v[8:9], v[14:15]
	v_and_b32_e32 v19, 0xffff0000, v5
	v_pk_add_f32 v[8:9], v[8:9], v[16:17]
	v_lshlrev_b32_e32 v22, 16, v7
	v_pk_add_f32 v[8:9], v[8:9], v[18:19]
	v_and_b32_e32 v23, 0xffff0000, v7
	v_and_b32_e32 v1, 0xffff, v25
	v_and_b32_e32 v3, 0xffff, v27
	v_pk_add_f32 v[8:9], v[8:9], v[20:21]
	v_lshrrev_b32_e32 v5, 16, v25
	v_lshrrev_b32_e32 v7, 16, v27
	v_lshl_or_b32 v0, v28, 16, v0
	v_lshl_or_b32 v1, v29, 16, v1
	v_lshl_or_b32 v2, v30, 16, v2
	v_lshl_or_b32 v3, v31, 16, v3
	v_exp_f32_e32 v32, v16
	v_exp_f32_e32 v34, v17
	v_pk_add_f32 v[16:17], v[8:9], v[22:23]
	v_and_or_b32 v4, v28, s88, v4
	v_and_or_b32 v5, v29, s88, v5
	v_and_or_b32 v6, v30, s88, v6
	v_and_or_b32 v7, v31, s88, v7
	ds_write_b64 v78, v[16:17] offset:56320
	ds_write_b128 v96, v[0:3] offset:37888
	ds_write_b128 v96, v[4:7] offset:38032
	s_waitcnt lgkmcnt(0)
	s_barrier
	ds_read2st64_b64 v[0:3], v82 offset0:110 offset1:111
	ds_read2st64_b64 v[4:7], v82 offset0:112 offset1:113
	v_exp_f32_e32 v25, v10
	v_exp_f32_e32 v27, v11
	ds_read2st64_b64 v[8:11], v82 offset0:114 offset1:115
	s_waitcnt lgkmcnt(2)
	v_pk_add_f32 v[0:1], v[0:1], 0 op_sel_hi:[1,0]
	v_exp_f32_e32 v28, v12
	v_exp_f32_e32 v30, v13
	v_exp_f32_e32 v29, v14
	v_exp_f32_e32 v31, v15
	v_exp_f32_e32 v33, v18
	v_cndmask_b32_e64 v18, 0, v2, s[6:7]
	ds_read2st64_b64 v[12:15], v82 offset0:116 offset1:117
	v_cndmask_b32_e64 v54, 0, v0, s[4:5]
	s_waitcnt lgkmcnt(2)
	v_cndmask_b32_e64 v36, 0, v4, s[8:9]
	v_cndmask_b32_e64 v55, 0, v1, s[4:5]
	v_pk_add_f32 v[0:1], v[0:1], v[2:3]
	v_add_f32_e32 v2, v54, v18
	v_cndmask_b32_e64 v38, 0, v6, s[10:11]
	v_add_f32_e32 v2, v2, v36
	s_waitcnt lgkmcnt(1)
	v_cndmask_b32_e64 v48, 0, v8, s[12:13]
	v_pk_add_f32 v[0:1], v[0:1], v[4:5]
	v_add_f32_e32 v2, v2, v38
	v_cndmask_b32_e64 v50, 0, v10, s[14:15]
	v_pk_add_f32 v[0:1], v[0:1], v[6:7]
	v_add_f32_e32 v2, v2, v48
	s_waitcnt lgkmcnt(0)
	v_cndmask_b32_e64 v52, 0, v12, s[16:17]
	v_pk_add_f32 v[0:1], v[0:1], v[8:9]
	v_add_f32_e32 v2, v2, v50
	v_pk_add_f32 v[0:1], v[0:1], v[10:11]
	v_add_f32_e32 v2, v2, v52
	v_cndmask_b32_e64 v4, 0, v14, s[18:19]
	v_pk_add_f32 v[0:1], v[0:1], v[12:13]
	v_add_f32_e32 v2, v2, v4
	v_pk_add_f32 v[0:1], v[0:1], v[14:15]
	v_add_f32_e32 v2, v16, v2
	v_exp_f32_e32 v35, v19
	v_exp_f32_e32 v19, v22
	v_cndmask_b32_e64 v22, 0, v3, s[6:7]
	v_sub_f32_e32 v2, v0, v2
	v_cndmask_b32_e64 v37, 0, v5, s[8:9]
	v_cndmask_b32_e64 v39, 0, v7, s[10:11]
	v_add_f32_e32 v3, v55, v22
	v_exp_f32_e32 v7, v2
	v_add_f32_e32 v3, v3, v37
	v_exp_f32_e32 v18, v20
	v_cndmask_b32_e64 v49, 0, v9, s[12:13]
	v_add_f32_e32 v3, v3, v39
	v_cndmask_b32_e64 v51, 0, v11, s[14:15]
	v_add_f32_e32 v3, v3, v49
	v_cndmask_b32_e64 v53, 0, v13, s[16:17]
	v_add_f32_e32 v3, v3, v51
	v_mul_f32_e32 v6, v19, v7
	v_add_f32_e32 v3, v3, v53
	v_cndmask_b32_e64 v4, 0, v15, s[18:19]
	v_mul_f32_e32 v5, v18, v6
	v_add_f32_e32 v3, v3, v4
	v_mul_f32_e32 v4, v33, v5
	v_add_f32_e32 v2, v17, v3
	v_mul_f32_e32 v13, v32, v4
	v_sub_f32_e32 v2, v1, v2
	v_mul_f32_e32 v12, v29, v13
	v_exp_f32_e32 v23, v23
	v_exp_f32_e32 v11, v2
	v_mul_f32_e32 v15, v28, v12
	v_exp_f32_e32 v22, v21
	v_pk_add_f32 v[8:9], v[28:29], 1.0 op_sel_hi:[1,0] neg_lo:[1,0] neg_hi:[1,0]
	v_pk_add_f32 v[2:3], v[24:25], 1.0 op_sel_hi:[1,0] neg_lo:[1,0] neg_hi:[1,0]
	v_mul_f32_e32 v14, v25, v15
	v_pk_mul_f32 v[2:3], v[2:3], v[14:15]
	v_pk_mul_f32 v[8:9], v[8:9], v[12:13]
	v_cvt_pk_bf16_f32 v2, v2, v3
	v_cvt_pk_bf16_f32 v3, v8, v9
	v_pk_add_f32 v[8:9], v[32:33], 1.0 op_sel_hi:[1,0] neg_lo:[1,0] neg_hi:[1,0]
	v_mul_f32_e32 v10, v23, v11
	v_pk_mul_f32 v[4:5], v[8:9], v[4:5]
	v_pk_add_f32 v[8:9], v[18:19], 1.0 op_sel_hi:[1,0] neg_lo:[1,0] neg_hi:[1,0]
	v_cvt_pk_bf16_f32 v4, v4, v5
	v_pk_mul_f32 v[6:7], v[8:9], v[6:7]
	v_mul_f32_e32 v9, v22, v10
	v_mul_f32_e32 v8, v35, v9
	v_mul_f32_e32 v15, v34, v8
	v_mul_f32_e32 v14, v31, v15
	v_mul_f32_e32 v17, v30, v14
	v_cvt_pk_bf16_f32 v5, v6, v7
	v_pk_add_f32 v[12:13], v[30:31], 1.0 op_sel_hi:[1,0] neg_lo:[1,0] neg_hi:[1,0]
	v_pk_add_f32 v[6:7], v[26:27], 1.0 op_sel_hi:[1,0] neg_lo:[1,0] neg_hi:[1,0]
	v_mul_f32_e32 v16, v27, v17
	v_pk_mul_f32 v[6:7], v[6:7], v[16:17]
	v_pk_mul_f32 v[12:13], v[12:13], v[14:15]
	v_cvt_pk_bf16_f32 v6, v6, v7
	v_cvt_pk_bf16_f32 v7, v12, v13
	v_pk_add_f32 v[12:13], v[34:35], 1.0 op_sel_hi:[1,0] neg_lo:[1,0] neg_hi:[1,0]
	s_nop 0
	v_pk_mul_f32 v[8:9], v[12:13], v[8:9]
	v_pk_add_f32 v[12:13], v[22:23], 1.0 op_sel_hi:[1,0] neg_lo:[1,0] neg_hi:[1,0]
	v_cvt_pk_bf16_f32 v8, v8, v9
	v_pk_mul_f32 v[10:11], v[12:13], v[10:11]
	s_nop 0
	v_cvt_pk_bf16_f32 v9, v10, v11
	v_add_u32_e32 v10, v234, v83
	ds_write_b128 v10, v[2:5]
	v_cndmask_b32_e64 v2, 0, 1, s[0:1]
	v_cmp_ne_u32_e64 s[20:21], 1, v2
	ds_write_b128 v10, v[6:9] offset:144
	s_cbranch_vccnz .LBB0_261
	v_exp_f32_e32 v2, v0
	v_exp_f32_e32 v3, v1
	v_add_u32_e32 v4, v83, v81
	ds_write_b64 v4, v[2:3] offset:18432

; #define LAS __attribute__((address_space(3)))
; #define MFMA16(a, b, c) __builtin_amdgcn_mfma_f32_16x16x32_bf16((a), (b), (c), 0, 0, 0)
; __device__ __forceinline__ void hgrn_r1(const GAS bf16* proj, GAS float* RU, GAS float* RD, int TOKG, unsigned char* lds, int tid, int lane, int wave, int bid, int G) {
;     ...
;         for (int ci = 0; ci < RUNC; ++ci) {
;             const bool nxt = ci + 1 < RUNC;
;             if (nxt) R1_P(ci + 1, ci + 2 < RUNC);
;             __syncthreads();
;             { const LAS unsigned char* Lv = L + VS0 + (ci % 3) * VSET; const LAS unsigned char* Lk = L + (ci & 1) * KSET; const LAS float* decl = (const LAS float*)(Lk + 128 * HS);
;               bf16x8 vf[2];
; #pragma unroll
;               for (int ks = 0; ks < 2; ++ks) vf[ks] = *(const LAS bf16x8*)(Lv + (16 * wave + fr) * HS + (32 * ks + 8 * fq) * 2);
; #pragma unroll
;               for (int nk = 0; nk < 8; ++nk) { const f32x4h dk = *(const LAS f32x4h*)(decl + 16 * nk + 4 * fq); acc[nk] = acc[nk] * dk;
; #pragma unroll
;                   for (int ks = 0; ks < 2; ++ks) { const bf16x8 kf = *(const LAS bf16x8*)(Lk + (16 * nk + fr) * HS + (32 * ks + 8 * fq) * 2); acc[nk] = MFMA16(kf, vf[ks], acc[nk]); } } }
.LBB0_263:
	s_waitcnt vmcnt(1)
	v_lshlrev_b32_e32 v36, 16, v58
	v_and_b32_e32 v37, 0xffff0000, v58
	v_lshlrev_b32_e32 v58, 16, v68
	s_mov_b32 s48, s42
	s_add_i32 s42, s42, 1
	v_and_or_b32 v98, v69, s89, v58
	v_lshlrev_b32_e32 v58, 16, v90
	s_mul_hi_u32 s27, s43, 0xaaaaaaab
	v_and_or_b32 v99, v91, s89, v58
	v_lshlrev_b32_e32 v58, 16, v92
	s_add_i32 s53, s42, s36
	s_lshr_b32 s27, s27, 1
	v_lshlrev_b32_e32 v38, 16, v65
	v_and_b32_e32 v39, 0xffff0000, v65
	v_and_or_b32 v100, v93, s89, v58
	s_waitcnt vmcnt(0)
	v_lshlrev_b32_e32 v58, 16, v94
	s_and_b32 s54, s39, 0x3f80000
	s_and_b32 s53, s53, 0x780
	s_mul_i32 s27, s27, 0x10800
	v_lshlrev_b32_e32 v66, 16, v64
	v_and_b32_e32 v67, 0xffff0000, v64
	v_pk_add_f32 v[32:33], v[38:39], 0 op_sel_hi:[1,0]
	v_and_or_b32 v101, v95, s89, v58
	v_lshrrev_b32_e32 v58, 16, v69
	s_and_b32 s55, s40, 0x7c000000
	s_or_b32 s53, s54, s53
	v_subrev_u32_e32 v52, s27, v85
	v_subrev_u32_e32 v53, s27, v86
	s_mul_hi_u32 s27, s38, 0xaaaaaaab
	v_lshlrev_b32_e32 v110, 16, v63
	v_and_b32_e32 v111, 0xffff0000, v63
	v_pk_add_f32 v[32:33], v[32:33], v[66:67]
	v_and_or_b32 v102, v68, s88, v58
	v_lshrrev_b32_e32 v58, 16, v91
	s_or_b32 s53, s53, s55
	s_lshr_b32 s49, s27, 1
	v_lshlrev_b32_e32 v56, 16, v62
	v_and_b32_e32 v57, 0xffff0000, v62
	v_pk_add_f32 v[32:33], v[32:33], v[110:111]
	v_and_or_b32 v103, v90, s88, v58
	v_lshrrev_b32_e32 v58, 16, v93
	s_lshl_b32 s53, s53, 1
	s_mul_i32 s49, s49, 0x10800
	v_lshlrev_b32_e32 v54, 16, v61
	v_and_b32_e32 v55, 0xffff0000, v61
	v_pk_add_f32 v[32:33], v[32:33], v[56:57]
	v_and_or_b32 v104, v92, s88, v58
	v_lshrrev_b32_e32 v58, 16, v95
	s_or_b32 s54, s53, 0x1000
	s_bitset1_b32 s53, 13
	s_sub_i32 s27, s30, s49
	v_lshlrev_b32_e32 v50, 16, v60
	v_and_b32_e32 v51, 0xffff0000, v60
	v_lshlrev_b32_e32 v34, 16, v59
	v_and_b32_e32 v35, 0xffff0000, v59
	v_pk_add_f32 v[32:33], v[32:33], v[54:55]
	v_and_or_b32 v105, v94, s88, v58
	buffer_load_dword v65, v70, s[44:47], s54 offen
	buffer_load_dword v69, v70, s[44:47], s53 offen
	buffer_load_dword v64, v71, s[44:47], s54 offen
	buffer_load_dword v68, v71, s[44:47], s53 offen
	buffer_load_dword v63, v72, s[44:47], s54 offen
	buffer_load_dword v91, v72, s[44:47], s53 offen
	buffer_load_dword v62, v73, s[44:47], s54 offen
	buffer_load_dword v90, v73, s[44:47], s53 offen
	buffer_load_dword v61, v74, s[44:47], s54 offen
	buffer_load_dword v93, v74, s[44:47], s53 offen
	buffer_load_dword v60, v75, s[44:47], s54 offen
	buffer_load_dword v92, v75, s[44:47], s53 offen
	buffer_load_dword v59, v76, s[44:47], s54 offen
	buffer_load_dword v95, v76, s[44:47], s53 offen
	buffer_load_dword v58, v77, s[44:47], s54 offen
	buffer_load_dword v94, v77, s[44:47], s53 offen
	s_add_i32 s53, s37, 0
	v_pk_add_f32 v[32:33], v[32:33], v[50:51]
	v_add_u32_e32 v128, s37, v87
	s_bitcmp1_b32 s42, 0
	v_subrev_u32_e32 v97, s49, v89
	v_pk_add_f32 v[32:33], v[32:33], v[34:35]
	v_add_u32_e32 v106, s27, v128
	s_cselect_b32 s27, 0x4a00, 0
	v_pk_add_f32 v[32:33], v[32:33], v[36:37]
	v_add_u32_e32 v97, s53, v97
	s_add_i32 s27, s27, 0
	ds_write_b64 v106, v[32:33]
	ds_write_b128 v97, v[98:101]
	ds_write_b128 v97, v[102:105] offset:144
	v_add_u32_e32 v97, s27, v112
	v_add_u32_e32 v129, v97, v43
	s_waitcnt lgkmcnt(0)
	s_barrier
	ds_read_b128 v[98:101], v129
	v_add_u32_e32 v53, s53, v53
	v_add_u32_e32 v52, s53, v52
	ds_read_b128 v[102:105], v97 offset:18432
	ds_read_b128 v[106:109], v53
	ds_read_b128 v[114:117], v52
	ds_read_b128 v[118:121], v129 offset:64
	ds_read_b128 v[122:125], v97 offset:18496
	s_waitcnt lgkmcnt(4)
	v_pk_mul_f32 v[28:29], v[28:29], v[102:103]
	v_pk_mul_f32 v[30:31], v[30:31], v[104:105]
	ds_read_b128 v[102:105], v129 offset:2368
	v_exp_f32_e32 v52, v38
	s_waitcnt lgkmcnt(4)
	v_mfma_f32_16x16x32_bf16 v[28:31], v[98:101], v[106:109], v[28:31]
	ds_read_b128 v[98:101], v129 offset:2304
	s_waitcnt lgkmcnt(2)
	v_pk_mul_f32 v[24:25], v[24:25], v[122:123]
	v_pk_mul_f32 v[26:27], v[26:27], v[124:125]
	v_mfma_f32_16x16x32_bf16 v[28:31], v[118:121], v[114:117], v[28:31]
	v_exp_f32_e32 v38, v39
	v_exp_f32_e32 v53, v66
	v_exp_f32_e32 v39, v67
	s_waitcnt lgkmcnt(0)
	v_mfma_f32_16x16x32_bf16 v[24:27], v[98:101], v[106:109], v[24:27]
	ds_read_b128 v[98:101], v129 offset:4608
	ds_read_b128 v[118:121], v97 offset:18560
	v_exp_f32_e32 v66, v110
	v_exp_f32_e32 v110, v111
	v_mfma_f32_16x16x32_bf16 v[24:27], v[102:105], v[114:117], v[24:27]
	ds_read_b128 v[102:105], v129 offset:4672
	ds_read_b128 v[122:125], v97 offset:18624
	s_waitcnt lgkmcnt(2)
	v_pk_mul_f32 v[20:21], v[20:21], v[118:119]
	v_pk_mul_f32 v[22:23], v[22:23], v[120:121]
	ds_read_b128 v[118:121], v129 offset:6912
	v_exp_f32_e32 v67, v56
	v_mfma_f32_16x16x32_bf16 v[20:23], v[98:101], v[106:109], v[20:23]
	ds_read_b128 v[98:101], v129 offset:6976
	s_waitcnt lgkmcnt(2)
	v_pk_mul_f32 v[16:17], v[16:17], v[122:123]
	v_pk_mul_f32 v[18:19], v[18:19], v[124:125]
	v_mfma_f32_16x16x32_bf16 v[20:23], v[102:105], v[114:117], v[20:23]
	v_exp_f32_e32 v111, v57
	v_exp_f32_e32 v126, v54
	v_subrev_u32_e32 v130, s49, v88
	s_waitcnt lgkmcnt(1)
	v_mfma_f32_16x16x32_bf16 v[16:19], v[118:121], v[106:109], v[16:19]
	ds_read_b128 v[102:105], v129 offset:9216
	ds_read_b128 v[118:121], v97 offset:18688
	v_exp_f32_e32 v127, v50
	s_bitcmp1_b32 s48, 0
	s_waitcnt lgkmcnt(2)
	v_mfma_f32_16x16x32_bf16 v[16:19], v[98:101], v[114:117], v[16:19]
	ds_read_b128 v[98:101], v129 offset:9280
	ds_read_b128 v[122:125], v97 offset:18752
	s_waitcnt lgkmcnt(2)
	v_pk_mul_f32 v[12:13], v[12:13], v[118:119]
	v_pk_mul_f32 v[14:15], v[14:15], v[120:121]
	ds_read_b128 v[118:121], v129 offset:11520
	s_cselect_b32 s48, 0x4a00, 0
	v_mfma_f32_16x16x32_bf16 v[12:15], v[102:105], v[106:109], v[12:15]
	ds_read_b128 v[102:105], v129 offset:11584
	s_waitcnt lgkmcnt(2)
; #define LAS __attribute__((address_space(3)))
; #define MFMA16(a, b, c) __builtin_amdgcn_mfma_f32_16x16x32_bf16((a), (b), (c), 0, 0, 0)
; __device__ __forceinline__ void hgrn_r1(const GAS bf16* proj, GAS float* RU, GAS float* RD, int TOKG, unsigned char* lds, int tid, int lane, int wave, int bid, int G) {
;     ...
;               for (int nk = 0; nk < 8; ++nk) { const f32x4h dk = *(const LAS f32x4h*)(decl + 16 * nk + 4 * fq); acc[nk] = acc[nk] * dk;
; #pragma unroll
;                   for (int ks = 0; ks < 2; ++ks) { const bf16x8 kf = *(const LAS bf16x8*)(Lk + (16 * nk + fr) * HS + (32 * ks + 8 * fq) * 2); acc[nk] = MFMA16(kf, vf[ks], acc[nk]); } } }
;             if (nxt) R1_B(ci + 1);
	v_pk_mul_f32 v[8:9], v[8:9], v[122:123]
	v_pk_mul_f32 v[10:11], v[10:11], v[124:125]
	v_mfma_f32_16x16x32_bf16 v[12:15], v[98:101], v[114:117], v[12:15]
	v_exp_f32_e32 v122, v55
	v_exp_f32_e32 v123, v51
	s_and_b64 vcc, exec, s[20:21]
	s_waitcnt lgkmcnt(1)
	v_mfma_f32_16x16x32_bf16 v[8:11], v[118:121], v[106:109], v[8:11]
	ds_read_b128 v[98:101], v129 offset:13824
	ds_read_b128 v[118:121], v97 offset:18816
	s_waitcnt lgkmcnt(0)
	v_pk_mul_f32 v[4:5], v[4:5], v[118:119]
	v_mfma_f32_16x16x32_bf16 v[8:11], v[102:105], v[114:117], v[8:11]
	ds_read_b128 v[54:57], v129 offset:13888
	ds_read_b128 v[102:105], v97 offset:18880
	v_pk_mul_f32 v[6:7], v[6:7], v[120:121]
	ds_read_b128 v[118:121], v129 offset:16128
	v_subrev_u32_e32 v97, s49, v128
	v_mfma_f32_16x16x32_bf16 v[4:7], v[98:101], v[106:109], v[4:7]
	ds_read_b128 v[98:101], v129 offset:16192
	s_waitcnt lgkmcnt(2)
	v_pk_mul_f32 v[0:1], v[0:1], v[102:103]
	v_pk_mul_f32 v[2:3], v[2:3], v[104:105]
	v_mfma_f32_16x16x32_bf16 v[4:7], v[54:57], v[114:117], v[4:7]
	v_exp_f32_e32 v56, v35
	v_add_u32_e32 v35, 0x13600, v97
	v_exp_f32_e32 v55, v36
	v_exp_f32_e32 v57, v37
	ds_read_b64 v[36:37], v35
	s_waitcnt lgkmcnt(2)
	v_mfma_f32_16x16x32_bf16 v[0:3], v[118:121], v[106:109], v[0:3]
	v_add_u32_e32 v35, 0x13800, v97
	v_exp_f32_e32 v54, v34
	v_add_u32_e32 v34, s53, v130
	s_waitcnt lgkmcnt(1)
	v_mfma_f32_16x16x32_bf16 v[0:3], v[98:101], v[114:117], v[0:3]
	v_add_u32_e32 v98, 0x13a00, v97
	ds_read_b64 v[50:51], v35
	ds_read_b64 v[98:99], v98
	ds_read_b64 v[100:101], v34
	v_add_u32_e32 v104, 0x13c00, v97
	ds_read_b64 v[108:109], v104
	v_add_u32_e32 v104, 0x13e00, v97
	v_add_u32_e32 v106, 0x14000, v97
	v_add_u32_e32 v97, 0x14200, v97
	s_waitcnt lgkmcnt(1)
	v_add_f32_e32 v140, 0, v100
	v_cndmask_b32_e64 v34, 0, v36, s[6:7]
	ds_read_b64 v[114:115], v104
	ds_read_b64 v[116:117], v106
	ds_read_b64 v[118:119], v97
	v_cndmask_b32_e64 v97, 0, v140, s[4:5]
	v_cndmask_b32_e64 v35, 0, v50, s[8:9]
	v_add_f32_e32 v141, v97, v34
	v_mov_b32_e32 v34, v36
	v_cndmask_b32_e64 v105, 0, v98, s[10:11]
	v_pk_add_f32 v[34:35], v[140:141], v[34:35]
	v_mov_b32_e32 v104, v50
	s_waitcnt lgkmcnt(3)
	v_cndmask_b32_e64 v121, 0, v108, s[12:13]
	v_pk_add_f32 v[34:35], v[34:35], v[104:105]
	v_mov_b32_e32 v120, v98
	s_waitcnt lgkmcnt(2)
	v_cndmask_b32_e64 v129, 0, v114, s[14:15]
	v_pk_add_f32 v[34:35], v[34:35], v[120:121]
	v_mov_b32_e32 v128, v108
	s_waitcnt lgkmcnt(1)
	v_cndmask_b32_e64 v133, 0, v116, s[16:17]
	v_pk_add_f32 v[34:35], v[34:35], v[128:129]
	v_mov_b32_e32 v132, v114
	s_waitcnt lgkmcnt(0)
	v_cndmask_b32_e64 v137, 0, v118, s[18:19]
	v_pk_add_f32 v[34:35], v[34:35], v[132:133]
	v_mov_b32_e32 v136, v116
	v_pk_add_f32 v[34:35], v[34:35], v[136:137]
	v_mov_b32_e32 v104, v118
	v_mov_b32_e32 v105, v32
	v_pk_add_f32 v[34:35], v[34:35], v[104:105]
	v_add_f32_e32 v100, 0, v101
	v_sub_f32_e32 v32, v34, v35
	v_cndmask_b32_e64 v102, 0, v37, s[6:7]
	v_exp_f32_e32 v105, v32
	v_cndmask_b32_e64 v32, 0, v100, s[4:5]
	v_cndmask_b32_e64 v103, 0, v51, s[8:9]
	v_add_f32_e32 v101, v32, v102
	v_mov_b32_e32 v102, v37
	v_cndmask_b32_e64 v107, 0, v99, s[10:11]
	v_pk_add_f32 v[36:37], v[100:101], v[102:103]
	v_mov_b32_e32 v106, v51
	v_cndmask_b32_e64 v125, 0, v109, s[12:13]
	v_pk_add_f32 v[36:37], v[36:37], v[106:107]
	v_mov_b32_e32 v124, v99
	v_cndmask_b32_e64 v131, 0, v115, s[14:15]
	v_pk_add_f32 v[36:37], v[36:37], v[124:125]
	v_mov_b32_e32 v130, v109
	v_cndmask_b32_e64 v135, 0, v117, s[16:17]
	v_pk_add_f32 v[36:37], v[36:37], v[130:131]
	v_mov_b32_e32 v134, v115
	v_cndmask_b32_e64 v139, 0, v119, s[18:19]
	v_pk_add_f32 v[36:37], v[36:37], v[134:135]
	v_mov_b32_e32 v138, v117
	v_pk_add_f32 v[36:37], v[36:37], v[138:139]
	v_mov_b32_e32 v32, v119
	v_mul_f32_e32 v104, v55, v105
	v_pk_add_f32 v[32:33], v[36:37], v[32:33]
	v_mul_f32_e32 v107, v54, v104
	v_sub_f32_e32 v33, v32, v33
	v_mul_f32_e32 v106, v127, v107
	v_exp_f32_e32 v99, v33
	v_mul_f32_e32 v109, v126, v106
	v_mul_f32_e32 v108, v67, v109
	v_mul_f32_e32 v51, v66, v108
	v_pk_add_f32 v[36:37], v[52:53], 1.0 op_sel_hi:[1,0] neg_lo:[1,0] neg_hi:[1,0]
	v_mul_f32_e32 v50, v53, v51
	v_mul_f32_e32 v98, v57, v99
	v_pk_add_f32 v[100:101], v[66:67], 1.0 op_sel_hi:[1,0] neg_lo:[1,0] neg_hi:[1,0]
	v_pk_mul_f32 v[36:37], v[36:37], v[50:51]
	v_pk_add_f32 v[102:103], v[126:127], 1.0 op_sel_hi:[1,0] neg_lo:[1,0] neg_hi:[1,0]
	v_cvt_pk_bf16_f32 v50, v36, v37
	v_pk_mul_f32 v[36:37], v[100:101], v[108:109]
	v_mul_f32_e32 v101, v56, v98
	v_mul_f32_e32 v100, v123, v101
	v_cvt_pk_bf16_f32 v51, v36, v37
	v_pk_mul_f32 v[36:37], v[102:103], v[106:107]
	v_mul_f32_e32 v103, v122, v100
	v_cvt_pk_bf16_f32 v52, v36, v37
	v_pk_add_f32 v[36:37], v[54:55], 1.0 op_sel_hi:[1,0] neg_lo:[1,0] neg_hi:[1,0]
	v_mul_f32_e32 v102, v111, v103
	v_pk_mul_f32 v[36:37], v[36:37], v[104:105]
	v_mul_f32_e32 v105, v110, v102
	v_cvt_pk_bf16_f32 v53, v36, v37
	v_pk_add_f32 v[36:37], v[38:39], 1.0 op_sel_hi:[1,0] neg_lo:[1,0] neg_hi:[1,0]
	v_pk_add_f32 v[54:55], v[110:111], 1.0 op_sel_hi:[1,0] neg_lo:[1,0] neg_hi:[1,0]
	v_mul_f32_e32 v104, v39, v105
	v_pk_add_f32 v[66:67], v[122:123], 1.0 op_sel_hi:[1,0] neg_lo:[1,0] neg_hi:[1,0]
	v_pk_mul_f32 v[36:37], v[36:37], v[104:105]
	v_pk_mul_f32 v[38:39], v[54:55], v[102:103]
	v_pk_add_f32 v[54:55], v[56:57], 1.0 op_sel_hi:[1,0] neg_lo:[1,0] neg_hi:[1,0]
	v_cvt_pk_bf16_f32 v36, v36, v37
	v_cvt_pk_bf16_f32 v37, v38, v39
	v_pk_mul_f32 v[38:39], v[66:67], v[100:101]
	v_pk_mul_f32 v[54:55], v[54:55], v[98:99]
	v_add_u32_e32 v33, s48, v80
	v_cvt_pk_bf16_f32 v38, v38, v39
	v_cvt_pk_bf16_f32 v39, v54, v55
	v_add_u32_e32 v35, v234, v33
	ds_write_b128 v35, v[50:53]
	ds_write_b128 v35, v[36:39] offset:144
	s_cbranch_vccnz .LBB0_262
	v_exp_f32_e32 v36, v34
	v_exp_f32_e32 v37, v32
	v_add_u32_e32 v33, v33, v81
	ds_write_b64 v33, v[36:37] offset:18432
	s_branch .LBB0_262
; #define LAS __attribute__((address_space(3)))
; #define MFMA16(a, b, c) __builtin_amdgcn_mfma_f32_16x16x32_bf16((a), (b), (c), 0, 0, 0)
; __device__ __forceinline__ void hgrn_r1(const GAS bf16* proj, GAS float* RU, GAS float* RD, int TOKG, unsigned char* lds, int tid, int lane, int wave, int bid, int G) {
;     ...
;         for (int ci = 0; ci < RUNC; ++ci) {
;             const bool nxt = ci + 1 < RUNC;
;             if (nxt) R1_P(ci + 1, ci + 2 < RUNC);
;             __syncthreads();
;             { const LAS unsigned char* Lv = L + VS0 + (ci % 3) * VSET; const LAS unsigned char* Lk = L + (ci & 1) * KSET; const LAS float* decl = (const LAS float*)(Lk + 128 * HS);
;               bf16x8 vf[2];
; #pragma unroll
;               for (int ks = 0; ks < 2; ++ks) vf[ks] = *(const LAS bf16x8*)(Lv + (16 * wave + fr) * HS + (32 * ks + 8 * fq) * 2);
; #pragma unroll
;               for (int nk = 0; nk < 8; ++nk) { const f32x4h dk = *(const LAS f32x4h*)(decl + 16 * nk + 4 * fq); acc[nk] = acc[nk] * dk;
; #pragma unroll
;                   for (int ks = 0; ks < 2; ++ks) { const bf16x8 kf = *(const LAS bf16x8*)(Lk + (16 * nk + fr) * HS + (32 * ks + 8 * fq) * 2); acc[nk] = MFMA16(kf, vf[ks], acc[nk]); } } }
.LBB0_265:
	s_waitcnt vmcnt(15)
	v_lshlrev_b32_e32 v32, 16, v65
	v_and_b32_e32 v33, 0xffff0000, v65
	s_waitcnt vmcnt(13)
	v_lshlrev_b32_e32 v34, 16, v64
	v_and_b32_e32 v35, 0xffff0000, v64
	v_pk_add_f32 v[52:53], v[32:33], 0 op_sel_hi:[1,0]
	s_waitcnt vmcnt(11)
	v_lshlrev_b32_e32 v36, 16, v63
	v_and_b32_e32 v37, 0xffff0000, v63
	v_exp_f32_e32 v54, v32
	v_exp_f32_e32 v50, v33
	v_pk_add_f32 v[32:33], v[52:53], v[34:35]
	s_waitcnt vmcnt(9)
	v_lshlrev_b32_e32 v38, 16, v62
	v_and_b32_e32 v39, 0xffff0000, v62
	v_pk_add_f32 v[32:33], v[32:33], v[36:37]
	s_waitcnt vmcnt(7)
	v_lshlrev_b32_e32 v56, 16, v61
	v_and_b32_e32 v57, 0xffff0000, v61
	v_pk_add_f32 v[32:33], v[32:33], v[38:39]
	s_waitcnt vmcnt(5)
	v_lshlrev_b32_e32 v64, 16, v60
	v_and_b32_e32 v65, 0xffff0000, v60
	v_pk_add_f32 v[32:33], v[32:33], v[56:57]
	s_waitcnt vmcnt(3)
	v_lshlrev_b32_e32 v66, 16, v59
	v_and_b32_e32 v67, 0xffff0000, v59
	v_pk_add_f32 v[32:33], v[32:33], v[64:65]
	s_waitcnt vmcnt(1)
	v_lshlrev_b32_e32 v98, 16, v58
	v_and_b32_e32 v99, 0xffff0000, v58
	v_pk_add_f32 v[32:33], v[32:33], v[66:67]
	v_exp_f32_e32 v55, v34
	v_exp_f32_e32 v51, v35
	v_exp_f32_e32 v60, v36
	v_exp_f32_e32 v52, v37
	v_exp_f32_e32 v61, v38
	v_exp_f32_e32 v53, v39
	v_exp_f32_e32 v63, v64
	v_exp_f32_e32 v64, v66
	v_exp_f32_e32 v58, v67
	v_pk_add_f32 v[66:67], v[32:33], v[98:99]
	v_lshlrev_b32_e32 v32, 16, v68
	v_lshlrev_b32_e32 v33, 16, v90
	v_lshlrev_b32_e32 v34, 16, v92
	s_waitcnt vmcnt(0)
	v_lshlrev_b32_e32 v35, 16, v94
	v_lshrrev_b32_e32 v36, 16, v69
	v_lshrrev_b32_e32 v37, 16, v91
	v_lshrrev_b32_e32 v38, 16, v93
	v_lshrrev_b32_e32 v39, 16, v95
	v_and_or_b32 v32, v69, s89, v32
	v_and_or_b32 v33, v91, s89, v33
	v_and_or_b32 v34, v93, s89, v34
	v_and_or_b32 v35, v95, s89, v35
	v_and_or_b32 v36, v68, s88, v36
	v_and_or_b32 v37, v90, s88, v37
	v_and_or_b32 v38, v92, s88, v38
	v_and_or_b32 v39, v94, s88, v39
	ds_write_b64 v78, v[66:67] offset:56320
	ds_write_b128 v96, v[32:35] offset:37888
	ds_write_b128 v96, v[36:39] offset:38032
	s_waitcnt lgkmcnt(0)
	s_barrier
	ds_read_b128 v[36:39], v84 offset:37888
	ds_read_b128 v[32:35], v84 offset:37952
	ds_read_b128 v[90:93], v40 offset:18432
	v_exp_f32_e32 v62, v56
	v_exp_f32_e32 v56, v57
	v_exp_f32_e32 v57, v65
	v_exp_f32_e32 v65, v98
	s_waitcnt lgkmcnt(0)
	v_pk_mul_f32 v[28:29], v[28:29], v[90:91]
	v_add_u32_e32 v90, v40, v43
	v_pk_mul_f32 v[30:31], v[30:31], v[92:93]
	ds_read_b128 v[92:95], v90
	v_exp_f32_e32 v59, v99
	s_waitcnt lgkmcnt(0)
	v_mfma_f32_16x16x32_bf16 v[28:31], v[92:95], v[36:39], v[28:31]
	ds_read_b128 v[92:95], v90 offset:64
	s_and_b64 vcc, exec, s[20:21]
	ds_read2st64_b64 v[96:99], v82 offset0:116 offset1:117
	s_waitcnt lgkmcnt(1)
	v_mfma_f32_16x16x32_bf16 v[28:31], v[92:95], v[32:35], v[28:31]
	ds_read_b128 v[92:95], v40 offset:18496
	s_waitcnt lgkmcnt(1)
	v_cndmask_b32_e64 v117, 0, v96, s[16:17]
	v_cndmask_b32_e64 v121, 0, v98, s[18:19]
	v_mov_b32_e32 v120, v96
	v_cndmask_b32_e64 v119, 0, v97, s[16:17]
	s_waitcnt lgkmcnt(0)
	v_pk_mul_f32 v[26:27], v[26:27], v[94:95]
	v_pk_mul_f32 v[24:25], v[24:25], v[92:93]
	ds_read_b128 v[92:95], v90 offset:2304
	v_cndmask_b32_e64 v123, 0, v99, s[18:19]
	s_waitcnt lgkmcnt(0)
	v_mfma_f32_16x16x32_bf16 v[24:27], v[92:95], v[36:39], v[24:27]
	ds_read_b128 v[92:95], v90 offset:2368
	v_mov_b32_e32 v122, v97
	s_waitcnt lgkmcnt(0)
	v_mfma_f32_16x16x32_bf16 v[24:27], v[92:95], v[32:35], v[24:27]
	ds_read_b128 v[92:95], v40 offset:18560
	s_waitcnt lgkmcnt(0)
	v_pk_mul_f32 v[22:23], v[22:23], v[94:95]
	v_pk_mul_f32 v[20:21], v[20:21], v[92:93]
	ds_read_b128 v[92:95], v90 offset:4608
	s_waitcnt lgkmcnt(0)
	v_mfma_f32_16x16x32_bf16 v[20:23], v[92:95], v[36:39], v[20:23]
	ds_read_b128 v[92:95], v90 offset:4672
	s_waitcnt lgkmcnt(0)
	v_mfma_f32_16x16x32_bf16 v[20:23], v[92:95], v[32:35], v[20:23]
	ds_read_b128 v[92:95], v40 offset:18624
	s_waitcnt lgkmcnt(0)
	v_pk_mul_f32 v[18:19], v[18:19], v[94:95]
	v_pk_mul_f32 v[16:17], v[16:17], v[92:93]
	ds_read_b128 v[92:95], v90 offset:6912
	s_waitcnt lgkmcnt(0)
	v_mfma_f32_16x16x32_bf16 v[16:19], v[92:95], v[36:39], v[16:19]
	ds_read_b128 v[92:95], v90 offset:6976
	s_waitcnt lgkmcnt(0)
	v_mfma_f32_16x16x32_bf16 v[16:19], v[92:95], v[32:35], v[16:19]
	ds_read_b128 v[92:95], v40 offset:18688
	s_waitcnt lgkmcnt(0)
	v_pk_mul_f32 v[14:15], v[14:15], v[94:95]
	v_pk_mul_f32 v[12:13], v[12:13], v[92:93]
	ds_read_b128 v[92:95], v90 offset:9216
	s_waitcnt lgkmcnt(0)
	v_mfma_f32_16x16x32_bf16 v[12:15], v[92:95], v[36:39], v[12:15]
	ds_read_b128 v[92:95], v90 offset:9280
	s_waitcnt lgkmcnt(0)
	v_mfma_f32_16x16x32_bf16 v[12:15], v[92:95], v[32:35], v[12:15]
	ds_read_b128 v[92:95], v40 offset:18752
	s_waitcnt lgkmcnt(0)
	v_pk_mul_f32 v[10:11], v[10:11], v[94:95]
	v_pk_mul_f32 v[8:9], v[8:9], v[92:93]
	ds_read_b128 v[92:95], v90 offset:11520
	s_waitcnt lgkmcnt(0)
; #define LAS __attribute__((address_space(3)))
; #define MFMA16(a, b, c) __builtin_amdgcn_mfma_f32_16x16x32_bf16((a), (b), (c), 0, 0, 0)
; __device__ __forceinline__ void hgrn_r1(const GAS bf16* proj, GAS float* RU, GAS float* RD, int TOKG, unsigned char* lds, int tid, int lane, int wave, int bid, int G) {
;     ...
;               for (int nk = 0; nk < 8; ++nk) { const f32x4h dk = *(const LAS f32x4h*)(decl + 16 * nk + 4 * fq); acc[nk] = acc[nk] * dk;
; #pragma unroll
;                   for (int ks = 0; ks < 2; ++ks) { const bf16x8 kf = *(const LAS bf16x8*)(Lk + (16 * nk + fr) * HS + (32 * ks + 8 * fq) * 2); acc[nk] = MFMA16(kf, vf[ks], acc[nk]); } } }
;             if (nxt) R1_B(ci + 1);
	v_mfma_f32_16x16x32_bf16 v[8:11], v[92:95], v[36:39], v[8:11]
	ds_read_b128 v[92:95], v90 offset:11584
	s_waitcnt lgkmcnt(0)
	v_mfma_f32_16x16x32_bf16 v[8:11], v[92:95], v[32:35], v[8:11]
	ds_read_b128 v[92:95], v40 offset:18816
	s_waitcnt lgkmcnt(0)
	v_pk_mul_f32 v[6:7], v[6:7], v[94:95]
	v_pk_mul_f32 v[4:5], v[4:5], v[92:93]
	ds_read_b128 v[92:95], v90 offset:13824
	s_waitcnt lgkmcnt(0)
	v_mfma_f32_16x16x32_bf16 v[4:7], v[92:95], v[36:39], v[4:7]
	ds_read_b128 v[92:95], v90 offset:13888
	s_waitcnt lgkmcnt(0)
	v_mfma_f32_16x16x32_bf16 v[4:7], v[92:95], v[32:35], v[4:7]
	ds_read_b128 v[92:95], v40 offset:18880
	s_waitcnt lgkmcnt(0)
	v_pk_mul_f32 v[2:3], v[2:3], v[94:95]
	v_pk_mul_f32 v[0:1], v[0:1], v[92:93]
	ds_read_b128 v[92:95], v90 offset:16128
	s_waitcnt lgkmcnt(0)
	v_mfma_f32_16x16x32_bf16 v[0:3], v[92:95], v[36:39], v[0:3]
	ds_read_b128 v[36:39], v90 offset:16192
	ds_read2st64_b64 v[92:95], v82 offset0:114 offset1:115
	s_waitcnt lgkmcnt(0)
	v_cndmask_b32_e64 v107, 0, v92, s[12:13]
	v_mfma_f32_16x16x32_bf16 v[0:3], v[36:39], v[32:35], v[0:3]
	ds_read2st64_b64 v[32:35], v82 offset0:110 offset1:111
	ds_read2st64_b64 v[36:39], v82 offset0:112 offset1:113
	v_cndmask_b32_e64 v111, 0, v94, s[14:15]
	v_mov_b32_e32 v110, v92
	v_mov_b32_e32 v116, v94
	s_waitcnt lgkmcnt(1)
	v_add_f32_e32 v124, 0, v32
	v_cndmask_b32_e64 v68, 0, v34, s[6:7]
	v_cndmask_b32_e64 v32, 0, v124, s[4:5]
	s_waitcnt lgkmcnt(0)
	v_cndmask_b32_e64 v69, 0, v36, s[8:9]
	v_add_f32_e32 v125, v32, v68
	v_mov_b32_e32 v68, v34
	v_cndmask_b32_e64 v103, 0, v38, s[10:11]
	v_pk_add_f32 v[68:69], v[124:125], v[68:69]
	v_mov_b32_e32 v102, v36
	v_pk_add_f32 v[68:69], v[68:69], v[102:103]
	v_mov_b32_e32 v106, v38
	v_pk_add_f32 v[68:69], v[68:69], v[106:107]
	v_mov_b32_e32 v102, v98
	v_pk_add_f32 v[68:69], v[68:69], v[110:111]
	v_mov_b32_e32 v103, v66
	v_pk_add_f32 v[68:69], v[68:69], v[116:117]
	v_cndmask_b32_e64 v91, 0, v35, s[6:7]
	v_pk_add_f32 v[68:69], v[68:69], v[120:121]
	v_cndmask_b32_e64 v101, 0, v37, s[8:9]
	v_pk_add_f32 v[68:69], v[68:69], v[102:103]
	v_mov_b32_e32 v100, v35
	v_sub_f32_e32 v32, v68, v69
	v_exp_f32_e32 v103, v32
	v_add_f32_e32 v32, 0, v33
	v_cndmask_b32_e64 v33, 0, v32, s[4:5]
	v_add_f32_e32 v33, v33, v91
	v_cndmask_b32_e64 v105, 0, v39, s[10:11]
	v_pk_add_f32 v[32:33], v[32:33], v[100:101]
	v_mov_b32_e32 v104, v37
	v_cndmask_b32_e64 v109, 0, v93, s[12:13]
	v_pk_add_f32 v[32:33], v[32:33], v[104:105]
	v_mov_b32_e32 v108, v39
	v_cndmask_b32_e64 v115, 0, v95, s[14:15]
	v_pk_add_f32 v[32:33], v[32:33], v[108:109]
	v_mov_b32_e32 v114, v93
	v_pk_add_f32 v[32:33], v[32:33], v[114:115]
	v_mov_b32_e32 v118, v95
	v_pk_add_f32 v[32:33], v[32:33], v[118:119]
	v_mov_b32_e32 v66, v99
	v_pk_add_f32 v[32:33], v[32:33], v[122:123]
	v_mul_f32_e32 v102, v65, v103
	v_pk_add_f32 v[66:67], v[32:33], v[66:67]
	v_mul_f32_e32 v93, v64, v102
	v_sub_f32_e32 v32, v66, v67
	v_exp_f32_e32 v33, v32
	v_mul_f32_e32 v92, v63, v93
	v_pk_add_f32 v[38:39], v[62:63], 1.0 op_sel_hi:[1,0] neg_lo:[1,0] neg_hi:[1,0]
	v_mul_f32_e32 v63, v62, v92
	v_mul_f32_e32 v32, v59, v33
	v_pk_add_f32 v[36:37], v[60:61], 1.0 op_sel_hi:[1,0] neg_lo:[1,0] neg_hi:[1,0]
	v_mul_f32_e32 v62, v61, v63
	v_mul_f32_e32 v61, v60, v62
	v_pk_mul_f32 v[36:37], v[36:37], v[62:63]
	v_mul_f32_e32 v63, v58, v32
	v_pk_add_f32 v[34:35], v[54:55], 1.0 op_sel_hi:[1,0] neg_lo:[1,0] neg_hi:[1,0]
	v_mul_f32_e32 v60, v55, v61
	v_mul_f32_e32 v62, v57, v63
	v_pk_mul_f32 v[34:35], v[34:35], v[60:61]
	v_pk_add_f32 v[60:61], v[56:57], 1.0 op_sel_hi:[1,0] neg_lo:[1,0] neg_hi:[1,0]
	v_mul_f32_e32 v57, v56, v62
	v_cvt_pk_bf16_f32 v34, v34, v35
	v_cvt_pk_bf16_f32 v35, v36, v37
	v_pk_mul_f32 v[36:37], v[38:39], v[92:93]
	v_pk_add_f32 v[38:39], v[64:65], 1.0 op_sel_hi:[1,0] neg_lo:[1,0] neg_hi:[1,0]
	v_mul_f32_e32 v56, v53, v57
	v_pk_mul_f32 v[38:39], v[38:39], v[102:103]
	v_pk_add_f32 v[54:55], v[52:53], 1.0 op_sel_hi:[1,0] neg_lo:[1,0] neg_hi:[1,0]
	v_mul_f32_e32 v53, v52, v56
	v_cvt_pk_bf16_f32 v36, v36, v37
	v_cvt_pk_bf16_f32 v37, v38, v39
	v_pk_add_f32 v[38:39], v[50:51], 1.0 op_sel_hi:[1,0] neg_lo:[1,0] neg_hi:[1,0]
	v_mul_f32_e32 v52, v51, v53
	v_pk_mul_f32 v[38:39], v[38:39], v[52:53]
	s_nop 0
	v_cvt_pk_bf16_f32 v50, v38, v39
	v_pk_mul_f32 v[38:39], v[54:55], v[56:57]
	s_nop 0
	v_cvt_pk_bf16_f32 v51, v38, v39
	v_pk_mul_f32 v[38:39], v[60:61], v[62:63]
	s_nop 0
	v_cvt_pk_bf16_f32 v52, v38, v39
	v_pk_add_f32 v[38:39], v[58:59], 1.0 op_sel_hi:[1,0] neg_lo:[1,0] neg_hi:[1,0]
	s_nop 0
	v_pk_mul_f32 v[32:33], v[38:39], v[32:33]
	s_nop 0
	v_cvt_pk_bf16_f32 v53, v32, v33
	v_add_u32_e32 v32, s27, v79
	v_add_u32_e32 v33, v234, v32
	ds_write_b128 v33, v[34:37]
	ds_write_b128 v33, v[50:53] offset:144
	s_cbranch_vccnz .LBB0_267
	v_exp_f32_e32 v34, v68
	v_exp_f32_e32 v35, v66
	v_add_u32_e32 v32, v32, v81
	ds_write_b64 v32, v[34:35] offset:18432
